# barrier 4 split too: every workgroup runs one ATT0-hosted transpose in the shadow of barrier 3; workgroups 0..159 run their second one after arriving at barrier 4 and poll for it afterwards (published
# speedup vs baseline: 1.0065x; 1.0054x over previous
.Lnb3_wait:
	v_readlane_b32 s15, v219, 30
	s_nop 1
	s_cmp_lt_u32 s15, 0x100
	s_cbranch_scc1 .Lnb3_skip
	v_mov_b32_e32 v1, s14
	s_mov_b32 s15, 0

.Lnb3_skip:
.LBB0_326:
	s_or_b64 exec, exec, s[4:5]
	v_readlane_b32 s0, v219, 9
	v_lshlrev_b32_e32 v20, 2, v149
	v_readlane_b32 s8, v219, 17
	v_readlane_b32 s9, v219, 18
	s_waitcnt lgkmcnt(0)
	s_barrier
	s_nop 2
	global_load_dword v0, v20, s[8:9]
	global_load_dword v1, v20, s[8:9] offset:256
	global_load_dword v2, v20, s[8:9] offset:512
	global_load_dword v3, v20, s[8:9] offset:768
	v_mbcnt_hi_u32_b32 v4, -1, v163
	v_and_b32_e32 v5, 64, v4
	v_xor_b32_e32 v6, 32, v4
	v_add_u32_e32 v5, 64, v5
	v_cmp_lt_i32_e32 vcc, v6, v5
	v_xor_b32_e32 v7, 16, v4
	v_xor_b32_e32 v8, 8, v4
	v_cndmask_b32_e32 v6, v4, v6, vcc
	v_lshlrev_b32_e32 v172, 2, v6
	v_cmp_lt_i32_e32 vcc, v7, v5
	v_xor_b32_e32 v9, 4, v4
	v_xor_b32_e32 v10, 2, v4
	v_cndmask_b32_e32 v7, v4, v7, vcc
	v_lshlrev_b32_e32 v173, 2, v7
	v_cmp_lt_i32_e32 vcc, v8, v5
	v_xor_b32_e32 v11, 1, v4
	s_nop 0
	s_cmp_ge_u32 s78, 0xa0
	s_cselect_b64 s[8:9], -1, 0
	v_readlane_b32 s1, v219, 10
	v_readlane_b32 s2, v219, 11
	v_readlane_b32 s3, v219, 12
	v_readlane_b32 s4, v219, 13
	v_readlane_b32 s5, v219, 14
	v_readlane_b32 s6, v219, 15
	v_readlane_b32 s7, v219, 16
	v_readlane_b32 s10, v219, 19
	v_readlane_b32 s11, v219, 20
	v_readlane_b32 s12, v219, 21
	v_readlane_b32 s13, v219, 22
	v_readlane_b32 s14, v219, 23
	v_readlane_b32 s15, v219, 24
	s_waitcnt vmcnt(2)
	v_mul_f32_e32 v6, v0, v1
	ds_bpermute_b32 v6, v172, v6
	s_waitcnt vmcnt(0)
	v_mul_f32_e32 v12, v2, v3
	ds_bpermute_b32 v12, v172, v12
	s_waitcnt lgkmcnt(1)
	v_fmac_f32_e32 v6, v0, v1
	ds_bpermute_b32 v0, v173, v6
	s_waitcnt lgkmcnt(1)
	v_fmac_f32_e32 v12, v2, v3
	ds_bpermute_b32 v1, v173, v12
	v_cndmask_b32_e32 v2, v4, v8, vcc
	v_lshlrev_b32_e32 v174, 2, v2
	s_waitcnt lgkmcnt(1)
	v_add_f32_e32 v0, v6, v0
	ds_bpermute_b32 v2, v174, v0
	s_waitcnt lgkmcnt(1)
	v_add_f32_e32 v1, v12, v1
	ds_bpermute_b32 v3, v174, v1
	v_cmp_lt_i32_e32 vcc, v9, v5
	s_waitcnt lgkmcnt(1)
	v_add_f32_e32 v0, v0, v2
	v_cndmask_b32_e32 v6, v4, v9, vcc
	v_lshlrev_b32_e32 v175, 2, v6
	s_waitcnt lgkmcnt(0)
	v_add_f32_e32 v1, v1, v3
	ds_bpermute_b32 v2, v175, v0
	ds_bpermute_b32 v3, v175, v1
	v_cmp_lt_i32_e32 vcc, v10, v5
	s_waitcnt lgkmcnt(1)
	v_add_f32_e32 v0, v0, v2
	v_cndmask_b32_e32 v6, v4, v10, vcc
	v_lshlrev_b32_e32 v176, 2, v6
	s_waitcnt lgkmcnt(0)
	v_add_f32_e32 v1, v1, v3
	ds_bpermute_b32 v2, v176, v0
	ds_bpermute_b32 v3, v176, v1
	v_cmp_lt_i32_e32 vcc, v11, v5
	s_waitcnt lgkmcnt(1)
	v_add_f32_e32 v21, v0, v2
	v_cndmask_b32_e32 v4, v4, v11, vcc
	v_lshlrev_b32_e32 v177, 2, v4
	s_waitcnt lgkmcnt(0)
	v_add_f32_e32 v22, v1, v3
	ds_bpermute_b32 v23, v177, v21
	ds_bpermute_b32 v24, v177, v22
	s_mov_b64 vcc, 0
	s_cbranch_vccnz .LBB0_347
	s_add_i32 s0, s78, 0xc0
	s_cmpk_gt_i32 s0, 0x1bf
	s_waitcnt lgkmcnt(0)
	s_barrier
	s_cbranch_scc1 .LBB0_346
	s_movk_i32 s1, 0x2100
	v_lshrrev_b32_e32 v25, 3, v149
	v_and_b32_e32 v4, 56, v144
	s_cmpk_eq_i32 s58, 0x100
	v_mad_u32_u24 v1, v148, s1, 0
	v_lshrrev_b32_e32 v0, 5, v149
	v_and_b32_e32 v2, 31, v168
	v_mul_u32_u24_e32 v3, 0x84, v4
	v_lshlrev_b32_e32 v7, 2, v25
	s_cselect_b64 s[6:7], -1, 0
	v_mov_b32_e32 v5, 0
	v_lshl_add_u32 v6, v2, 2, v1
	s_movk_i32 s1, 0x84
	v_add3_u32 v26, v1, v3, v7
	v_or_b32_e32 v27, 8, v25
	v_or_b32_e32 v28, 16, v25
	v_or_b32_e32 v29, 24, v25
	v_mov_b32_e32 v1, v0
	s_movk_i32 s2, 0x187f
	s_movk_i32 s3, 0x1ff
	s_movk_i32 s10, 0xcff
	v_lshlrev_b32_e32 v8, 2, v2
	v_lshlrev_b32_e32 v10, 1, v4
	v_mov_b32_e32 v30, 0xffffe780
	v_mov_b32_e32 v31, 0xc00
	v_mov_b32_e32 v32, 0x600
	v_mov_b32_e32 v33, 0x2c0000
	v_mov_b32_e32 v34, 0x1400000
	v_mov_b32_e32 v35, 0x2980000
	v_mov_b32_e32 v36, 0x900000
	v_mov_b32_e32 v37, 0x1e80000
	v_mov_b32_e32 v38, 0x700000
	v_mov_b32_e32 v39, 0x1c80000
	v_mov_b32_e32 v40, 0x100000
	v_mov_b32_e32 v41, 0x1980000
	s_branch .LBB0_330
.LBB0_329:
	s_add_i32 s0, s0, s58
	s_cmpk_lt_i32 s0, 0x1c0
	s_cbranch_scc0 .LBB0_346

.LBB0_347:
	v_readlane_b32 s87, v219, 30
	s_nop 1
	s_cmp_ge_u32 s87, 0x100
	s_cbranch_scc1 .Latt0_dp_skip
	s_mov_b64 s[80:81], exec
	v_readlane_b32 s82, v219, 25
	v_readlane_b32 s83, v219, 26
	s_nop 1
	s_and_b64 s[82:83], s[80:81], s[82:83]
	s_mov_b64 exec, s[82:83]
	s_cbranch_execz .Latt0_dp_join
	v_readlane_b32 s82, v219, 27
	v_readlane_b32 s83, v219, 28
	v_readlane_b32 s84, v219, 29
	s_nop 1
	s_lshl_b32 s84, s84, 8
	s_add_i32 s84, s84, 0x2400
	v_mov_b32_e32 v223, s84
	s_mov_b32 s85, 0
	s_nop 3

.LBB0_375:
	s_waitcnt vmcnt(0) lgkmcnt(0)
	s_barrier
	s_mov_b64 s[80:81], exec
	v_readlane_b32 s82, v219, 25
	v_readlane_b32 s83, v219, 26
	s_nop 1
	s_and_b64 s[82:83], s[80:81], s[82:83]
	s_mov_b64 exec, s[82:83]
	s_cbranch_execz .Lb4a_join
	v_readlane_b32 s84, v219, 27
	v_readlane_b32 s85, v219, 28
	v_readlane_b32 s86, v219, 29
	v_mov_b32_e32 v221, 0x24000
	s_waitcnt vmcnt(0) lgkmcnt(0)
	buffer_inv sc1
	ds_read_b32 v223, v221
	ds_read_b32 v221, v221 offset:4
	s_lshl_b32 s87, s86, 8
	s_add_i32 s91, s87, 0x2400
	s_add_i32 s87, s87, 0x1400
	v_mov_b32_e32 v222, s87
	s_waitcnt lgkmcnt(0)
	v_readfirstlane_b32 s88, v223
	v_readfirstlane_b32 s89, v221
	v_mov_b32_e32 v221, 1
	s_nop 1
	global_atomic_add v223, v222, v221, s[84:85] sc0
	s_mul_i32 s88, s88, 3
	s_mul_i32 s89, s89, 3
	s_waitcnt vmcnt(0)
	v_readfirstlane_b32 s90, v223
	s_nop 1
	s_add_i32 s90, s90, 1
	s_cmp_lg_u32 s90, s88
	s_cbranch_scc1 .Lb4a_join
	v_mov_b32_e32 v222, 0x3400
	global_atomic_add v223, v222, v221, s[84:85] sc0
	s_waitcnt vmcnt(0)
	v_readfirstlane_b32 s90, v223
	s_nop 1
	s_add_i32 s90, s90, 1
	s_cmp_lg_u32 s90, s89
	s_cbranch_scc1 .Lb4a_join
	v_mov_b32_e32 v222, 0x2400
	global_atomic_add v222, v221, s[84:85]
	global_atomic_add v222, v221, s[84:85] offset:256
	global_atomic_add v222, v221, s[84:85] offset:512
	global_atomic_add v222, v221, s[84:85] offset:768
	global_atomic_add v222, v221, s[84:85] offset:1024
	global_atomic_add v222, v221, s[84:85] offset:1280
	global_atomic_add v222, v221, s[84:85] offset:1536
	global_atomic_add v222, v221, s[84:85] offset:1792
	global_atomic_add v222, v221, s[84:85] offset:2048
	global_atomic_add v222, v221, s[84:85] offset:2304
	global_atomic_add v222, v221, s[84:85] offset:2560
	global_atomic_add v222, v221, s[84:85] offset:2816
	global_atomic_add v222, v221, s[84:85] offset:3072
	global_atomic_add v222, v221, s[84:85] offset:3328
	global_atomic_add v222, v221, s[84:85] offset:3584
	global_atomic_add v222, v221, s[84:85] offset:3840
.Lb4a_join:
	s_mov_b64 exec, s[80:81]
	s_mov_b64 vcc, exec
	s_cbranch_vccz .LBB0_396
	s_add_i32 s0, s78, 0x1c0
	s_cmpk_gt_i32 s0, 0x25f
	s_waitcnt lgkmcnt(0)
	s_barrier
	s_cbranch_scc1 .LBB0_395
	s_movk_i32 s1, 0x2100
	v_lshrrev_b32_e32 v20, 3, v149
	v_and_b32_e32 v4, 56, v144
	s_cmpk_eq_i32 s58, 0x100
	v_mad_u32_u24 v1, v148, s1, 0
	v_lshrrev_b32_e32 v0, 5, v149
	v_and_b32_e32 v2, 31, v168
	v_mul_u32_u24_e32 v3, 0x84, v4
	v_lshlrev_b32_e32 v7, 2, v20
	s_cselect_b64 s[6:7], -1, 0
	v_mov_b32_e32 v5, 0
	v_lshl_add_u32 v6, v2, 2, v1
	s_movk_i32 s1, 0x84
	v_add3_u32 v21, v1, v3, v7
	v_or_b32_e32 v22, 8, v20
	v_or_b32_e32 v23, 16, v20
	v_or_b32_e32 v24, 24, v20
	v_mov_b32_e32 v1, v0
	s_movk_i32 s2, 0x187f
	s_movk_i32 s3, 0x1ff
	s_movk_i32 s10, 0xcff
	v_lshlrev_b32_e32 v8, 2, v2
	v_lshlrev_b32_e32 v10, 1, v4
	v_mov_b32_e32 v25, 0xffffe780
	v_mov_b32_e32 v26, 0xc00
	v_mov_b32_e32 v27, 0x600
	v_mov_b32_e32 v28, 0x2c0000
	v_mov_b32_e32 v29, 0x1400000
	v_mov_b32_e32 v30, 0x2980000
	v_mov_b32_e32 v31, 0x900000
	v_mov_b32_e32 v32, 0x1e80000
	v_mov_b32_e32 v33, 0x700000
	v_mov_b32_e32 v34, 0x1c80000
	v_mov_b32_e32 v35, 0x100000
	v_mov_b32_e32 v36, 0x1980000
	s_branch .LBB0_379

.LBB0_396:
	s_waitcnt vmcnt(0)
	s_waitcnt lgkmcnt(0)
	s_barrier
	s_mov_b64 s[4:5], exec
	v_readlane_b32 s0, v219, 25
	v_readlane_b32 s1, v219, 26
	s_and_b64 s[0:1], s[4:5], s[0:1]
	s_mov_b64 exec, s[0:1]
	s_cbranch_execz .LBB0_448
	v_readlane_b32 s0, v219, 27
	v_readlane_b32 s1, v219, 28
	v_readlane_b32 s2, v219, 29
	v_readlane_b32 s3, v219, 30
	s_waitcnt vmcnt(0) lgkmcnt(0)
	s_cmp_ge_u32 s3, 0xa0
	s_cbranch_scc1 .Lb4p_nol
	v_mov_b32_e32 v0, 1
	v_mov_b32_e32 v1, 0x10c0
	s_nop 3
	global_atomic_add v1, v0, s[0:1]
.Lb4p_nol:
	s_lshl_b32 s14, s2, 8
	s_add_i32 s14, s14, 0x2400
	v_mov_b32_e32 v1, s14
	s_mov_b32 s15, 0
	s_nop 3

.Lgb6_done:
	v_mov_b32_e32 v1, 0x10c0
	s_mov_b32 s15, 0
.Lgb6_spin2:
	global_load_dword v2, v1, s[0:1] sc1
	s_waitcnt vmcnt(0)
	v_readfirstlane_b32 s13, v2
	s_nop 1
	s_cmp_ge_u32 s13, 160
	s_cbranch_scc1 .Lgb6_done2
	s_sleep 4
	s_add_i32 s15, s15, 1
	s_cmp_lt_u32 s15, 0x200000
	s_cbranch_scc1 .Lgb6_spin2
